# speedup vs baseline: 1.0422x; 1.0036x over previous
; #define PG_LD(T, TAB, ST) do { const int st_ = (ST); _Pragma("unroll") for (int k = 0; k < 16; ++k) { const int e = __builtin_amdgcn_readlane(st_ < 4 ? i0 : i1, (st_ * 16 + k) & 63); \
;       T[k] = __builtin_bit_cast(u32x2, __builtin_amdgcn_raw_buffer_load_b64(TAB, lane * 8, e * 512, 0)); } } while (0)
; DEVI void peer_gather_phase(const Params& p, int layer, char* lds) {
;     ...
;     for (int b2 = 0; b2 < 4; ++b2) {
;       PG_LD(tb, srV, 2 * b2 + 1);
;       PG_AXPY(ta, 2 * b2);
;       if (b2 < 3) PG_LD(ta, srV, 2 * b2 + 2);
;       else if (hasn) {
; #pragma unroll
;         for (int k = 0; k < 16; ++k) { const int e = __builtin_amdgcn_readlane(i0n, k); ta[k] = __builtin_bit_cast(u32x2, __builtin_amdgcn_raw_buffer_load_b64(srU, lane * 8, e * 512, 0)); }
;       }
.LBB0_141:
	s_cmp_lt_u32 s1, 2
	s_cselect_b64 vcc, -1, 0
	v_cndmask_b32_e32 v10, v148, v147, vcc
	s_add_i32 s2, s0, 16
	v_readlane_b32 s2, v10, s2
	s_lshl_b32 s2, s2, 9
	s_nop 3
	buffer_load_dwordx2 v[114:115], v142, s[48:51], s2 offen
	s_add_i32 s2, s0, 17
	v_readlane_b32 s2, v10, s2
	s_lshl_b32 s2, s2, 9
	s_nop 3
	buffer_load_dwordx2 v[60:61], v142, s[48:51], s2 offen
	s_add_i32 s2, s0, 18
	v_readlane_b32 s2, v10, s2
	s_lshl_b32 s2, s2, 9
	s_nop 3
	buffer_load_dwordx2 v[54:55], v142, s[48:51], s2 offen
	s_add_i32 s2, s0, 19
	v_readlane_b32 s2, v10, s2
	s_lshl_b32 s2, s2, 9
	s_nop 3
	buffer_load_dwordx2 v[56:57], v142, s[48:51], s2 offen
	s_add_i32 s2, s0, 20
	v_readlane_b32 s2, v10, s2
	s_lshl_b32 s2, s2, 9
	s_nop 3
	buffer_load_dwordx2 v[50:51], v142, s[48:51], s2 offen
	s_add_i32 s2, s0, 21
	v_readlane_b32 s2, v10, s2
	s_lshl_b32 s2, s2, 9
	s_nop 3
	buffer_load_dwordx2 v[48:49], v142, s[48:51], s2 offen
	s_add_i32 s2, s0, 22
	v_readlane_b32 s2, v10, s2
	s_lshl_b32 s2, s2, 9
	s_nop 3
	buffer_load_dwordx2 v[42:43], v142, s[48:51], s2 offen
	s_add_i32 s2, s0, 23
	v_readlane_b32 s2, v10, s2
	s_lshl_b32 s2, s2, 9
	s_nop 3
	buffer_load_dwordx2 v[44:45], v142, s[48:51], s2 offen
	s_add_i32 s2, s0, 24
	v_readlane_b32 s2, v10, s2
	s_lshl_b32 s2, s2, 9
	s_nop 3
	buffer_load_dwordx2 v[40:41], v142, s[48:51], s2 offen
	s_add_i32 s2, s0, 25
	v_readlane_b32 s2, v10, s2
	s_lshl_b32 s2, s2, 9
	s_nop 3
	buffer_load_dwordx2 v[38:39], v142, s[48:51], s2 offen
	s_add_i32 s2, s0, 26
	v_readlane_b32 s2, v10, s2
	s_lshl_b32 s2, s2, 9
	s_nop 3
	buffer_load_dwordx2 v[34:35], v142, s[48:51], s2 offen
	s_add_i32 s2, s0, 27
	v_readlane_b32 s2, v10, s2
	s_lshl_b32 s2, s2, 9
	s_nop 3
	buffer_load_dwordx2 v[36:37], v142, s[48:51], s2 offen
	s_add_i32 s2, s0, 28
	v_readlane_b32 s2, v10, s2
	s_lshl_b32 s2, s2, 9
	s_nop 3
	buffer_load_dwordx2 v[32:33], v142, s[48:51], s2 offen
	s_add_i32 s2, s0, 29
	v_readlane_b32 s2, v10, s2
	s_lshl_b32 s2, s2, 9
	s_nop 3
	buffer_load_dwordx2 v[30:31], v142, s[48:51], s2 offen
	s_add_i32 s2, s0, 30
	v_readlane_b32 s2, v10, s2
	s_lshl_b32 s2, s2, 9
	s_nop 3
	buffer_load_dwordx2 v[26:27], v142, s[48:51], s2 offen
	s_add_i32 s2, s0, 31
	v_readlane_b32 s2, v10, s2
	s_lshl_b32 s2, s2, 9
	s_cmpk_eq_i32 s0, 0x60
	s_nop 2
	buffer_load_dwordx2 v[28:29], v142, s[48:51], s2 offen
	ds_read_b128 v[22:25], v63
	ds_read_b128 v[18:21], v63 offset:16
	s_waitcnt vmcnt(16)
	v_mov_b64_e32 v[140:141], v[82:83]
	v_mov_b64_e32 v[138:139], v[86:87]
	v_mov_b64_e32 v[136:137], v[84:85]
	v_mov_b64_e32 v[134:135], v[88:89]
	v_mov_b64_e32 v[132:133], v[94:95]
	v_mov_b64_e32 v[130:131], v[92:93]
	v_mov_b64_e32 v[128:129], v[90:91]
	v_mov_b64_e32 v[126:127], v[96:97]
	v_mov_b64_e32 v[124:125], v[102:103]
	v_mov_b64_e32 v[122:123], v[100:101]
	v_mov_b64_e32 v[120:121], v[98:99]
	v_mov_b64_e32 v[118:119], v[104:105]
	v_mov_b64_e32 v[116:117], v[108:109]
	v_mov_b64_e32 v[58:59], v[106:107]
	v_mov_b64_e32 v[52:53], v[110:111]
	v_mov_b64_e32 v[46:47], v[112:113]
	ds_read_b128 v[14:17], v63 offset:32
	ds_read_b128 v[10:13], v63 offset:48
	s_cbranch_scc1 .LBB0_144
	s_cmp_eq_u32 s0, 0
	s_cselect_b64 vcc, -1, 0
	v_cndmask_b32_e32 v112, v148, v147, vcc
	s_xor_b32 s2, s0, 32
	v_readlane_b32 s2, v112, s2
	s_xor_b32 s3, s0, 33
	s_xor_b32 s22, s0, 34
	s_xor_b32 s23, s0, 35
	s_lshl_b32 s2, s2, 9
	v_readlane_b32 s3, v112, s3
	v_readlane_b32 s22, v112, s22
	v_readlane_b32 s23, v112, s23
	s_lshl_b32 s3, s3, 9
	s_lshl_b32 s22, s22, 9
	s_lshl_b32 s23, s23, 9
	buffer_load_dwordx2 v[82:83], v142, s[48:51], s2 offen
	buffer_load_dwordx2 v[86:87], v142, s[48:51], s3 offen
	buffer_load_dwordx2 v[84:85], v142, s[48:51], s22 offen
	buffer_load_dwordx2 v[88:89], v142, s[48:51], s23 offen
	s_xor_b32 s2, s0, 36
	v_readlane_b32 s2, v112, s2
	s_xor_b32 s3, s0, 37
	s_xor_b32 s22, s0, 38
	s_xor_b32 s23, s0, 39
	s_lshl_b32 s2, s2, 9
	v_readlane_b32 s3, v112, s3
	v_readlane_b32 s22, v112, s22
	v_readlane_b32 s23, v112, s23
	s_lshl_b32 s3, s3, 9
	s_lshl_b32 s22, s22, 9
	s_lshl_b32 s23, s23, 9
	buffer_load_dwordx2 v[94:95], v142, s[48:51], s2 offen
	buffer_load_dwordx2 v[92:93], v142, s[48:51], s3 offen
	buffer_load_dwordx2 v[90:91], v142, s[48:51], s22 offen
	buffer_load_dwordx2 v[96:97], v142, s[48:51], s23 offen
	s_xor_b32 s2, s0, 40
	v_readlane_b32 s2, v112, s2
	s_xor_b32 s3, s0, 41
	s_xor_b32 s22, s0, 42
	s_xor_b32 s23, s0, 43
	s_lshl_b32 s2, s2, 9
	v_readlane_b32 s3, v112, s3
	v_readlane_b32 s22, v112, s22
	v_readlane_b32 s23, v112, s23
	s_lshl_b32 s3, s3, 9
	s_lshl_b32 s22, s22, 9
	s_lshl_b32 s23, s23, 9
	buffer_load_dwordx2 v[102:103], v142, s[48:51], s2 offen
	buffer_load_dwordx2 v[100:101], v142, s[48:51], s3 offen
	buffer_load_dwordx2 v[98:99], v142, s[48:51], s22 offen
	buffer_load_dwordx2 v[104:105], v142, s[48:51], s23 offen
	s_xor_b32 s2, s0, 44
	v_readlane_b32 s2, v112, s2
	s_xor_b32 s3, s0, 45
	s_xor_b32 s22, s0, 46
	s_lshl_b32 s2, s2, 9
	v_readlane_b32 s3, v112, s3
	v_readlane_b32 s22, v112, s22
	s_lshl_b32 s3, s3, 9
	s_lshl_b32 s22, s22, 9
	buffer_load_dwordx2 v[108:109], v142, s[48:51], s2 offen
	s_nop 0
	buffer_load_dwordx2 v[106:107], v142, s[48:51], s3 offen
	buffer_load_dwordx2 v[110:111], v142, s[48:51], s22 offen
	s_xor_b32 s2, s0, 47
	v_readlane_b32 s37, v112, s2
	s_mov_b64 s[2:3], -1
	s_cbranch_execz .LBB0_145
	s_mov_b64 s[52:53], s[48:49]
	s_mov_b64 s[54:55], s[50:51]
	v_mov_b64_e32 v[112:113], v[46:47]
	s_and_saveexec_b64 s[22:23], s[2:3]
	s_cbranch_execnz .LBB0_148
	s_branch .LBB0_149

; DEVI void peer_gather_phase(const Params& p, int layer, char* lds) {
;     ...
;       else if (hasn) {
; #pragma unroll
;         for (int k = 0; k < 16; ++k) { const int e = __builtin_amdgcn_readlane(i0n, k); ta[k] = __builtin_bit_cast(u32x2, __builtin_amdgcn_raw_buffer_load_b64(srU, lane * 8, e * 512, 0)); }
;       }
.LBB0_145:
	s_waitcnt vmcnt(16)
	v_mov_b64_e32 v[110:111], v[52:53]
	v_mov_b64_e32 v[106:107], v[58:59]
	v_mov_b64_e32 v[108:109], v[116:117]
	v_mov_b64_e32 v[104:105], v[118:119]
	v_mov_b64_e32 v[98:99], v[120:121]
	v_mov_b64_e32 v[100:101], v[122:123]
	v_mov_b64_e32 v[102:103], v[124:125]
	v_mov_b64_e32 v[96:97], v[126:127]
	v_mov_b64_e32 v[90:91], v[128:129]
	v_mov_b64_e32 v[92:93], v[130:131]
	v_mov_b64_e32 v[94:95], v[132:133]
	v_mov_b64_e32 v[88:89], v[134:135]
	v_mov_b64_e32 v[84:85], v[136:137]
	v_mov_b64_e32 v[86:87], v[138:139]
	v_mov_b64_e32 v[82:83], v[140:141]
	s_mov_b64 s[22:23], exec
	v_readlane_b32 s37, v146, 0
	s_lshl_b32 s37, s37, 9
	s_or_b64 s[2:3], s[2:3], exec
	s_nop 2
	buffer_load_dwordx2 v[82:83], v142, s[24:27], s37 offen
	v_readlane_b32 s37, v146, 1
	s_lshl_b32 s37, s37, 9
	s_nop 3
	buffer_load_dwordx2 v[86:87], v142, s[24:27], s37 offen
	v_readlane_b32 s37, v146, 2
	s_lshl_b32 s37, s37, 9
	s_nop 3
	buffer_load_dwordx2 v[84:85], v142, s[24:27], s37 offen
	v_readlane_b32 s37, v146, 3
	s_lshl_b32 s37, s37, 9
	s_nop 3
	buffer_load_dwordx2 v[88:89], v142, s[24:27], s37 offen
	v_readlane_b32 s37, v146, 4
	s_lshl_b32 s37, s37, 9
	s_nop 3
	buffer_load_dwordx2 v[94:95], v142, s[24:27], s37 offen
	v_readlane_b32 s37, v146, 5
	s_lshl_b32 s37, s37, 9
	s_nop 3
	buffer_load_dwordx2 v[92:93], v142, s[24:27], s37 offen
	v_readlane_b32 s37, v146, 6
	s_lshl_b32 s37, s37, 9
	s_nop 3
	buffer_load_dwordx2 v[90:91], v142, s[24:27], s37 offen
	v_readlane_b32 s37, v146, 7
	s_lshl_b32 s37, s37, 9
	s_nop 3
	buffer_load_dwordx2 v[96:97], v142, s[24:27], s37 offen
	v_readlane_b32 s37, v146, 8
	s_lshl_b32 s37, s37, 9
	s_nop 3
	buffer_load_dwordx2 v[102:103], v142, s[24:27], s37 offen
	v_readlane_b32 s37, v146, 9
	s_lshl_b32 s37, s37, 9
	s_nop 3
	buffer_load_dwordx2 v[100:101], v142, s[24:27], s37 offen
	v_readlane_b32 s37, v146, 10
	s_lshl_b32 s37, s37, 9
	s_nop 3
	buffer_load_dwordx2 v[98:99], v142, s[24:27], s37 offen
	v_readlane_b32 s37, v146, 11
	s_lshl_b32 s37, s37, 9
	s_nop 3
	buffer_load_dwordx2 v[104:105], v142, s[24:27], s37 offen
	v_readlane_b32 s37, v146, 12
	s_lshl_b32 s37, s37, 9
	s_nop 3
	buffer_load_dwordx2 v[108:109], v142, s[24:27], s37 offen
	v_readlane_b32 s37, v146, 13
	s_lshl_b32 s37, s37, 9
	s_nop 3
	buffer_load_dwordx2 v[106:107], v142, s[24:27], s37 offen
	v_readlane_b32 s37, v146, 14
	s_lshl_b32 s37, s37, 9
	s_nop 3
	buffer_load_dwordx2 v[110:111], v142, s[24:27], s37 offen
	v_readlane_b32 s37, v146, 15

.LBB0_149:
	s_or_b64 exec, exec, s[22:23]
	v_cvt_scalef32_pk_f16_fp4 v157, v140, 1.0
	s_waitcnt lgkmcnt(3)
	v_pk_fma_f16 v155, v157, v22, v155
	v_cvt_scalef32_pk_f16_fp4 v157, v140, 1.0 op_sel:[1,0,0]
	v_pk_fma_f16 v156, v157, v22, v156
	v_cvt_scalef32_pk_f16_fp4 v157, v140, 1.0 op_sel:[0,1,0]
	v_cvt_scalef32_pk_f16_fp4 v140, v140, 1.0 op_sel:[1,1,0]
	v_pk_fma_f16 v140, v140, v22, v153
	v_cvt_scalef32_pk_f16_fp4 v153, v141, 1.0
	v_pk_fma_f16 v152, v153, v22, v152
	v_cvt_scalef32_pk_f16_fp4 v153, v141, 1.0 op_sel:[1,0,0]
	v_pk_fma_f16 v151, v153, v22, v151
	v_cvt_scalef32_pk_f16_fp4 v153, v141, 1.0 op_sel:[0,1,0]
	v_cvt_scalef32_pk_f16_fp4 v141, v141, 1.0 op_sel:[1,1,0]
	v_pk_fma_f16 v154, v157, v22, v154
	v_pk_fma_f16 v150, v153, v22, v150
	v_pk_fma_f16 v22, v141, v22, v149
	v_cvt_scalef32_pk_f16_fp4 v141, v138, 1.0
	v_cvt_scalef32_pk_f16_fp4 v149, v138, 1.0 op_sel:[1,0,0]
	v_cvt_scalef32_pk_f16_fp4 v153, v138, 1.0 op_sel:[0,1,0]
	v_cvt_scalef32_pk_f16_fp4 v138, v138, 1.0 op_sel:[1,1,0]
	v_pk_fma_f16 v138, v138, v23, v140
	v_cvt_scalef32_pk_f16_fp4 v140, v139, 1.0
	v_pk_fma_f16 v140, v140, v23, v152
	v_cvt_scalef32_pk_f16_fp4 v152, v139, 1.0 op_sel:[1,0,0]
	v_pk_fma_f16 v151, v152, v23, v151
	v_cvt_scalef32_pk_f16_fp4 v152, v139, 1.0 op_sel:[0,1,0]
	v_cvt_scalef32_pk_f16_fp4 v139, v139, 1.0 op_sel:[1,1,0]
	v_pk_fma_f16 v141, v141, v23, v155
	v_pk_fma_f16 v149, v149, v23, v156
	v_pk_fma_f16 v153, v153, v23, v154
	v_pk_fma_f16 v150, v152, v23, v150
	v_pk_fma_f16 v22, v139, v23, v22
	v_cvt_scalef32_pk_f16_fp4 v23, v136, 1.0
	v_pk_fma_f16 v23, v23, v24, v141
	v_cvt_scalef32_pk_f16_fp4 v139, v136, 1.0 op_sel:[1,0,0]
	v_cvt_scalef32_pk_f16_fp4 v141, v136, 1.0 op_sel:[0,1,0]
	v_cvt_scalef32_pk_f16_fp4 v136, v136, 1.0 op_sel:[1,1,0]
	v_pk_fma_f16 v136, v136, v24, v138
	v_cvt_scalef32_pk_f16_fp4 v138, v137, 1.0
	v_pk_fma_f16 v139, v139, v24, v149
	v_pk_fma_f16 v138, v138, v24, v140
	v_cvt_scalef32_pk_f16_fp4 v140, v137, 1.0 op_sel:[1,0,0]
	v_cvt_scalef32_pk_f16_fp4 v149, v137, 1.0 op_sel:[0,1,0]
	v_cvt_scalef32_pk_f16_fp4 v137, v137, 1.0 op_sel:[1,1,0]
	v_pk_fma_f16 v141, v141, v24, v153
	v_pk_fma_f16 v140, v140, v24, v151
	v_pk_fma_f16 v149, v149, v24, v150
	v_pk_fma_f16 v22, v137, v24, v22
	v_cvt_scalef32_pk_f16_fp4 v24, v134, 1.0
	v_pk_fma_f16 v23, v24, v25, v23
	v_cvt_scalef32_pk_f16_fp4 v24, v134, 1.0 op_sel:[1,0,0]
	v_cvt_scalef32_pk_f16_fp4 v137, v134, 1.0 op_sel:[0,1,0]
	v_cvt_scalef32_pk_f16_fp4 v134, v134, 1.0 op_sel:[1,1,0]
	v_pk_fma_f16 v134, v134, v25, v136
	v_cvt_scalef32_pk_f16_fp4 v136, v135, 1.0
	v_pk_fma_f16 v24, v24, v25, v139
	v_pk_fma_f16 v136, v136, v25, v138
	v_cvt_scalef32_pk_f16_fp4 v138, v135, 1.0 op_sel:[1,0,0]
	v_cvt_scalef32_pk_f16_fp4 v139, v135, 1.0 op_sel:[0,1,0]
	v_cvt_scalef32_pk_f16_fp4 v135, v135, 1.0 op_sel:[1,1,0]
	v_pk_fma_f16 v137, v137, v25, v141
	v_pk_fma_f16 v138, v138, v25, v140
	v_pk_fma_f16 v139, v139, v25, v149
	v_pk_fma_f16 v22, v135, v25, v22
	v_cvt_scalef32_pk_f16_fp4 v25, v132, 1.0
	s_waitcnt lgkmcnt(2)
	v_pk_fma_f16 v23, v25, v18, v23
	v_cvt_scalef32_pk_f16_fp4 v25, v132, 1.0 op_sel:[1,0,0]
	v_pk_fma_f16 v24, v25, v18, v24
	v_cvt_scalef32_pk_f16_fp4 v25, v132, 1.0 op_sel:[0,1,0]
	v_cvt_scalef32_pk_f16_fp4 v132, v132, 1.0 op_sel:[1,1,0]
	v_pk_fma_f16 v132, v132, v18, v134
	v_cvt_scalef32_pk_f16_fp4 v134, v133, 1.0
	v_pk_fma_f16 v134, v134, v18, v136
	v_cvt_scalef32_pk_f16_fp4 v135, v133, 1.0 op_sel:[1,0,0]
	v_cvt_scalef32_pk_f16_fp4 v136, v133, 1.0 op_sel:[0,1,0]
	v_cvt_scalef32_pk_f16_fp4 v133, v133, 1.0 op_sel:[1,1,0]
	v_pk_fma_f16 v25, v25, v18, v137
	v_pk_fma_f16 v135, v135, v18, v138
	v_pk_fma_f16 v136, v136, v18, v139
	v_pk_fma_f16 v18, v133, v18, v22
	v_cvt_scalef32_pk_f16_fp4 v22, v130, 1.0
	v_pk_fma_f16 v22, v22, v19, v23
	v_cvt_scalef32_pk_f16_fp4 v23, v130, 1.0 op_sel:[1,0,0]
	v_pk_fma_f16 v23, v23, v19, v24
	v_cvt_scalef32_pk_f16_fp4 v24, v130, 1.0 op_sel:[0,1,0]
	v_pk_fma_f16 v24, v24, v19, v25
	v_cvt_scalef32_pk_f16_fp4 v25, v130, 1.0 op_sel:[1,1,0]
	v_pk_fma_f16 v25, v25, v19, v132
	v_cvt_scalef32_pk_f16_fp4 v130, v131, 1.0
	v_cvt_scalef32_pk_f16_fp4 v132, v131, 1.0 op_sel:[1,0,0]
	v_cvt_scalef32_pk_f16_fp4 v133, v131, 1.0 op_sel:[0,1,0]
	v_cvt_scalef32_pk_f16_fp4 v131, v131, 1.0 op_sel:[1,1,0]
	v_pk_fma_f16 v130, v130, v19, v134
	v_pk_fma_f16 v132, v132, v19, v135
	v_pk_fma_f16 v133, v133, v19, v136
	v_pk_fma_f16 v18, v131, v19, v18
	v_cvt_scalef32_pk_f16_fp4 v19, v128, 1.0
	v_pk_fma_f16 v19, v19, v20, v22
	v_cvt_scalef32_pk_f16_fp4 v22, v128, 1.0 op_sel:[1,0,0]
	v_pk_fma_f16 v22, v22, v20, v23
	v_cvt_scalef32_pk_f16_fp4 v23, v128, 1.0 op_sel:[0,1,0]
	v_pk_fma_f16 v23, v23, v20, v24
	v_cvt_scalef32_pk_f16_fp4 v24, v128, 1.0 op_sel:[1,1,0]
	v_pk_fma_f16 v24, v24, v20, v25
	v_cvt_scalef32_pk_f16_fp4 v25, v129, 1.0
	v_pk_fma_f16 v25, v25, v20, v130
	v_cvt_scalef32_pk_f16_fp4 v128, v129, 1.0 op_sel:[1,0,0]
	v_cvt_scalef32_pk_f16_fp4 v130, v129, 1.0 op_sel:[0,1,0]
	v_cvt_scalef32_pk_f16_fp4 v129, v129, 1.0 op_sel:[1,1,0]
	v_pk_fma_f16 v128, v128, v20, v132
	v_pk_fma_f16 v130, v130, v20, v133
	v_pk_fma_f16 v18, v129, v20, v18
	v_cvt_scalef32_pk_f16_fp4 v20, v126, 1.0
	v_pk_fma_f16 v19, v20, v21, v19
	v_cvt_scalef32_pk_f16_fp4 v20, v126, 1.0 op_sel:[1,0,0]
	v_pk_fma_f16 v20, v20, v21, v22
	v_cvt_scalef32_pk_f16_fp4 v22, v126, 1.0 op_sel:[0,1,0]
	v_pk_fma_f16 v22, v22, v21, v23
	v_cvt_scalef32_pk_f16_fp4 v23, v126, 1.0 op_sel:[1,1,0]
	v_pk_fma_f16 v23, v23, v21, v24
	v_cvt_scalef32_pk_f16_fp4 v24, v127, 1.0
	v_pk_fma_f16 v24, v24, v21, v25
	v_cvt_scalef32_pk_f16_fp4 v25, v127, 1.0 op_sel:[1,0,0]
	v_cvt_scalef32_pk_f16_fp4 v126, v127, 1.0 op_sel:[0,1,0]
	v_cvt_scalef32_pk_f16_fp4 v127, v127, 1.0 op_sel:[1,1,0]
	v_pk_fma_f16 v25, v25, v21, v128
	v_pk_fma_f16 v126, v126, v21, v130
	v_pk_fma_f16 v18, v127, v21, v18
	v_cvt_scalef32_pk_f16_fp4 v21, v124, 1.0
	s_waitcnt lgkmcnt(1)
	v_pk_fma_f16 v19, v21, v14, v19
	v_cvt_scalef32_pk_f16_fp4 v21, v124, 1.0 op_sel:[1,0,0]
	v_pk_fma_f16 v20, v21, v14, v20
	v_cvt_scalef32_pk_f16_fp4 v21, v124, 1.0 op_sel:[0,1,0]
	v_pk_fma_f16 v21, v21, v14, v22
	v_cvt_scalef32_pk_f16_fp4 v22, v124, 1.0 op_sel:[1,1,0]
	v_pk_fma_f16 v22, v22, v14, v23
	v_cvt_scalef32_pk_f16_fp4 v23, v125, 1.0
	v_pk_fma_f16 v23, v23, v14, v24
	v_cvt_scalef32_pk_f16_fp4 v24, v125, 1.0 op_sel:[1,0,0]
	v_pk_fma_f16 v24, v24, v14, v25
	v_cvt_scalef32_pk_f16_fp4 v25, v125, 1.0 op_sel:[0,1,0]
	v_cvt_scalef32_pk_f16_fp4 v124, v125, 1.0 op_sel:[1,1,0]
	v_pk_fma_f16 v25, v25, v14, v126
	v_pk_fma_f16 v14, v124, v14, v18
	v_cvt_scalef32_pk_f16_fp4 v18, v122, 1.0
	v_pk_fma_f16 v18, v18, v15, v19
	v_cvt_scalef32_pk_f16_fp4 v19, v122, 1.0 op_sel:[1,0,0]
	v_pk_fma_f16 v19, v19, v15, v20
	v_cvt_scalef32_pk_f16_fp4 v20, v122, 1.0 op_sel:[0,1,0]
	v_pk_fma_f16 v20, v20, v15, v21
	v_cvt_scalef32_pk_f16_fp4 v21, v122, 1.0 op_sel:[1,1,0]
	v_pk_fma_f16 v21, v21, v15, v22
	v_cvt_scalef32_pk_f16_fp4 v22, v123, 1.0
	v_pk_fma_f16 v22, v22, v15, v23
	v_cvt_scalef32_pk_f16_fp4 v23, v123, 1.0 op_sel:[1,0,0]
	v_pk_fma_f16 v23, v23, v15, v24
	v_cvt_scalef32_pk_f16_fp4 v24, v123, 1.0 op_sel:[0,1,0]
	v_pk_fma_f16 v24, v24, v15, v25
	v_cvt_scalef32_pk_f16_fp4 v25, v123, 1.0 op_sel:[1,1,0]
	v_pk_fma_f16 v14, v25, v15, v14
	v_cvt_scalef32_pk_f16_fp4 v15, v120, 1.0
	v_pk_fma_f16 v15, v15, v16, v18
	v_cvt_scalef32_pk_f16_fp4 v18, v120, 1.0 op_sel:[1,0,0]
	v_pk_fma_f16 v18, v18, v16, v19
	v_cvt_scalef32_pk_f16_fp4 v19, v120, 1.0 op_sel:[0,1,0]
	v_pk_fma_f16 v19, v19, v16, v20
	v_cvt_scalef32_pk_f16_fp4 v20, v120, 1.0 op_sel:[1,1,0]
	v_pk_fma_f16 v20, v20, v16, v21
	v_cvt_scalef32_pk_f16_fp4 v21, v121, 1.0
	v_pk_fma_f16 v21, v21, v16, v22
	v_cvt_scalef32_pk_f16_fp4 v22, v121, 1.0 op_sel:[1,0,0]
	v_pk_fma_f16 v22, v22, v16, v23
	v_cvt_scalef32_pk_f16_fp4 v23, v121, 1.0 op_sel:[0,1,0]
	v_pk_fma_f16 v23, v23, v16, v24
	v_cvt_scalef32_pk_f16_fp4 v24, v121, 1.0 op_sel:[1,1,0]
	v_pk_fma_f16 v14, v24, v16, v14
	v_cvt_scalef32_pk_f16_fp4 v16, v118, 1.0
	v_pk_fma_f16 v15, v16, v17, v15
	v_cvt_scalef32_pk_f16_fp4 v16, v118, 1.0 op_sel:[1,0,0]
	v_pk_fma_f16 v16, v16, v17, v18
	v_cvt_scalef32_pk_f16_fp4 v18, v118, 1.0 op_sel:[0,1,0]
	v_pk_fma_f16 v18, v18, v17, v19
	v_cvt_scalef32_pk_f16_fp4 v19, v118, 1.0 op_sel:[1,1,0]
	v_pk_fma_f16 v19, v19, v17, v20
	v_cvt_scalef32_pk_f16_fp4 v20, v119, 1.0
	v_pk_fma_f16 v20, v20, v17, v21
	v_cvt_scalef32_pk_f16_fp4 v21, v119, 1.0 op_sel:[1,0,0]
	v_pk_fma_f16 v21, v21, v17, v22
	v_cvt_scalef32_pk_f16_fp4 v22, v119, 1.0 op_sel:[0,1,0]
	v_pk_fma_f16 v22, v22, v17, v23
	v_cvt_scalef32_pk_f16_fp4 v23, v119, 1.0 op_sel:[1,1,0]
	v_pk_fma_f16 v14, v23, v17, v14
	v_cvt_scalef32_pk_f16_fp4 v17, v116, 1.0
	s_waitcnt lgkmcnt(0)
	v_pk_fma_f16 v15, v17, v10, v15
	v_cvt_scalef32_pk_f16_fp4 v17, v116, 1.0 op_sel:[1,0,0]
	v_pk_fma_f16 v16, v17, v10, v16
	v_cvt_scalef32_pk_f16_fp4 v17, v116, 1.0 op_sel:[0,1,0]
	v_pk_fma_f16 v17, v17, v10, v18
	v_cvt_scalef32_pk_f16_fp4 v18, v116, 1.0 op_sel:[1,1,0]
	v_pk_fma_f16 v18, v18, v10, v19
	v_cvt_scalef32_pk_f16_fp4 v19, v117, 1.0
	v_pk_fma_f16 v19, v19, v10, v20
	v_cvt_scalef32_pk_f16_fp4 v20, v117, 1.0 op_sel:[1,0,0]
	v_pk_fma_f16 v20, v20, v10, v21
	v_cvt_scalef32_pk_f16_fp4 v21, v117, 1.0 op_sel:[0,1,0]
	v_pk_fma_f16 v21, v21, v10, v22
	v_cvt_scalef32_pk_f16_fp4 v22, v117, 1.0 op_sel:[1,1,0]
	v_pk_fma_f16 v10, v22, v10, v14
	v_cvt_scalef32_pk_f16_fp4 v14, v58, 1.0
	v_pk_fma_f16 v14, v14, v11, v15
	v_cvt_scalef32_pk_f16_fp4 v15, v58, 1.0 op_sel:[1,0,0]
	v_pk_fma_f16 v15, v15, v11, v16
	v_cvt_scalef32_pk_f16_fp4 v16, v58, 1.0 op_sel:[0,1,0]
	v_pk_fma_f16 v16, v16, v11, v17
	v_cvt_scalef32_pk_f16_fp4 v17, v58, 1.0 op_sel:[1,1,0]
	v_pk_fma_f16 v17, v17, v11, v18
	v_cvt_scalef32_pk_f16_fp4 v18, v59, 1.0
	v_pk_fma_f16 v18, v18, v11, v19
	v_cvt_scalef32_pk_f16_fp4 v19, v59, 1.0 op_sel:[1,0,0]
	v_pk_fma_f16 v19, v19, v11, v20
	v_cvt_scalef32_pk_f16_fp4 v20, v59, 1.0 op_sel:[0,1,0]
	v_pk_fma_f16 v20, v20, v11, v21
	v_cvt_scalef32_pk_f16_fp4 v21, v59, 1.0 op_sel:[1,1,0]
	v_pk_fma_f16 v10, v21, v11, v10
	v_cvt_scalef32_pk_f16_fp4 v11, v52, 1.0
	v_pk_fma_f16 v11, v11, v12, v14
	v_cvt_scalef32_pk_f16_fp4 v14, v52, 1.0 op_sel:[1,0,0]
	v_pk_fma_f16 v14, v14, v12, v15
	v_cvt_scalef32_pk_f16_fp4 v15, v52, 1.0 op_sel:[0,1,0]
	v_pk_fma_f16 v15, v15, v12, v16
	v_cvt_scalef32_pk_f16_fp4 v16, v52, 1.0 op_sel:[1,1,0]
	v_pk_fma_f16 v16, v16, v12, v17
	v_cvt_scalef32_pk_f16_fp4 v17, v53, 1.0
	v_pk_fma_f16 v17, v17, v12, v18
	v_cvt_scalef32_pk_f16_fp4 v18, v53, 1.0 op_sel:[1,0,0]
	v_pk_fma_f16 v18, v18, v12, v19
	v_cvt_scalef32_pk_f16_fp4 v19, v53, 1.0 op_sel:[0,1,0]
	v_pk_fma_f16 v19, v19, v12, v20
	v_cvt_scalef32_pk_f16_fp4 v20, v53, 1.0 op_sel:[1,1,0]
	v_pk_fma_f16 v10, v20, v12, v10
	v_cvt_scalef32_pk_f16_fp4 v12, v46, 1.0
	v_pk_fma_f16 v52, v12, v13, v11
	v_cvt_scalef32_pk_f16_fp4 v11, v46, 1.0 op_sel:[1,0,0]
	v_pk_fma_f16 v53, v11, v13, v14
	v_cvt_scalef32_pk_f16_fp4 v11, v46, 1.0 op_sel:[0,1,0]
	v_pk_fma_f16 v58, v11, v13, v15
	v_cvt_scalef32_pk_f16_fp4 v11, v46, 1.0 op_sel:[1,1,0]
	v_pk_fma_f16 v46, v11, v13, v16
	v_cvt_scalef32_pk_f16_fp4 v11, v47, 1.0
	v_pk_fma_f16 v59, v11, v13, v17
	v_cvt_scalef32_pk_f16_fp4 v11, v47, 1.0 op_sel:[1,0,0]
	v_pk_fma_f16 v116, v11, v13, v18
	v_cvt_scalef32_pk_f16_fp4 v11, v47, 1.0 op_sel:[0,1,0]
	v_pk_fma_f16 v117, v11, v13, v19
	v_cvt_scalef32_pk_f16_fp4 v11, v47, 1.0 op_sel:[1,1,0]
	v_pk_fma_f16 v47, v11, v13, v10
	ds_read_b128 v[14:17], v63 offset:64
	ds_read_b128 v[18:21], v63 offset:80
	ds_read_b128 v[22:25], v63 offset:96
	ds_read_b128 v[10:13], v63 offset:112
	s_waitcnt vmcnt(31)
; DEVI void peer_gather_phase(const Params& p, int layer, char* lds) {
;     ...
;       PG_AXPY(tb, 2 * b2 + 1);
	v_cvt_scalef32_pk_f16_fp4 v118, v114, 1.0
	s_waitcnt lgkmcnt(3)
	v_pk_fma_f16 v52, v118, v14, v52
	v_cvt_scalef32_pk_f16_fp4 v118, v114, 1.0 op_sel:[1,0,0]
	v_pk_fma_f16 v53, v118, v14, v53
	v_cvt_scalef32_pk_f16_fp4 v118, v114, 1.0 op_sel:[0,1,0]
	v_cvt_scalef32_pk_f16_fp4 v114, v114, 1.0 op_sel:[1,1,0]
	v_pk_fma_f16 v46, v114, v14, v46
	v_cvt_scalef32_pk_f16_fp4 v114, v115, 1.0
	v_pk_fma_f16 v59, v114, v14, v59
	v_cvt_scalef32_pk_f16_fp4 v114, v115, 1.0 op_sel:[1,0,0]
	v_pk_fma_f16 v114, v114, v14, v116
	v_cvt_scalef32_pk_f16_fp4 v116, v115, 1.0 op_sel:[0,1,0]
	v_cvt_scalef32_pk_f16_fp4 v115, v115, 1.0 op_sel:[1,1,0]
	v_pk_fma_f16 v58, v118, v14, v58
	v_pk_fma_f16 v116, v116, v14, v117
	v_pk_fma_f16 v14, v115, v14, v47
	s_waitcnt vmcnt(30)
	v_cvt_scalef32_pk_f16_fp4 v47, v60, 1.0
	v_pk_fma_f16 v47, v47, v15, v52
	v_cvt_scalef32_pk_f16_fp4 v52, v60, 1.0 op_sel:[1,0,0]
	v_pk_fma_f16 v52, v52, v15, v53
	v_cvt_scalef32_pk_f16_fp4 v53, v60, 1.0 op_sel:[0,1,0]
	v_pk_fma_f16 v53, v53, v15, v58
	v_cvt_scalef32_pk_f16_fp4 v58, v60, 1.0 op_sel:[1,1,0]
	v_pk_fma_f16 v46, v58, v15, v46
	v_cvt_scalef32_pk_f16_fp4 v58, v61, 1.0
	v_pk_fma_f16 v58, v58, v15, v59
	v_cvt_scalef32_pk_f16_fp4 v59, v61, 1.0 op_sel:[1,0,0]
	v_cvt_scalef32_pk_f16_fp4 v60, v61, 1.0 op_sel:[0,1,0]
	v_cvt_scalef32_pk_f16_fp4 v61, v61, 1.0 op_sel:[1,1,0]
	v_pk_fma_f16 v59, v59, v15, v114
	v_pk_fma_f16 v60, v60, v15, v116
	v_pk_fma_f16 v14, v61, v15, v14
	s_waitcnt vmcnt(29)
	v_cvt_scalef32_pk_f16_fp4 v15, v54, 1.0
	v_pk_fma_f16 v15, v15, v16, v47
	v_cvt_scalef32_pk_f16_fp4 v47, v54, 1.0 op_sel:[1,0,0]
	v_pk_fma_f16 v47, v47, v16, v52
	v_cvt_scalef32_pk_f16_fp4 v52, v54, 1.0 op_sel:[0,1,0]
	v_pk_fma_f16 v52, v52, v16, v53
	v_cvt_scalef32_pk_f16_fp4 v53, v54, 1.0 op_sel:[1,1,0]
	v_pk_fma_f16 v46, v53, v16, v46
	v_cvt_scalef32_pk_f16_fp4 v53, v55, 1.0
	v_pk_fma_f16 v53, v53, v16, v58
	v_cvt_scalef32_pk_f16_fp4 v54, v55, 1.0 op_sel:[1,0,0]
	v_cvt_scalef32_pk_f16_fp4 v58, v55, 1.0 op_sel:[0,1,0]
	v_cvt_scalef32_pk_f16_fp4 v55, v55, 1.0 op_sel:[1,1,0]
	v_pk_fma_f16 v54, v54, v16, v59
	v_pk_fma_f16 v58, v58, v16, v60
	v_pk_fma_f16 v14, v55, v16, v14
	s_waitcnt vmcnt(28)
	v_cvt_scalef32_pk_f16_fp4 v16, v56, 1.0
	v_pk_fma_f16 v15, v16, v17, v15
	v_cvt_scalef32_pk_f16_fp4 v16, v56, 1.0 op_sel:[1,0,0]
	v_pk_fma_f16 v16, v16, v17, v47
	v_cvt_scalef32_pk_f16_fp4 v47, v56, 1.0 op_sel:[0,1,0]
	v_pk_fma_f16 v47, v47, v17, v52
	v_cvt_scalef32_pk_f16_fp4 v52, v56, 1.0 op_sel:[1,1,0]
	v_pk_fma_f16 v46, v52, v17, v46
	v_cvt_scalef32_pk_f16_fp4 v52, v57, 1.0
	v_pk_fma_f16 v52, v52, v17, v53
	v_cvt_scalef32_pk_f16_fp4 v53, v57, 1.0 op_sel:[1,0,0]
	v_pk_fma_f16 v53, v53, v17, v54
	v_cvt_scalef32_pk_f16_fp4 v54, v57, 1.0 op_sel:[0,1,0]
	v_cvt_scalef32_pk_f16_fp4 v55, v57, 1.0 op_sel:[1,1,0]
	v_pk_fma_f16 v54, v54, v17, v58
	v_pk_fma_f16 v14, v55, v17, v14
	s_waitcnt vmcnt(27)
	v_cvt_scalef32_pk_f16_fp4 v17, v50, 1.0
	s_waitcnt lgkmcnt(2)
	v_pk_fma_f16 v15, v17, v18, v15
	v_cvt_scalef32_pk_f16_fp4 v17, v50, 1.0 op_sel:[1,0,0]
	v_pk_fma_f16 v16, v17, v18, v16
	v_cvt_scalef32_pk_f16_fp4 v17, v50, 1.0 op_sel:[0,1,0]
	v_pk_fma_f16 v17, v17, v18, v47
	v_cvt_scalef32_pk_f16_fp4 v47, v50, 1.0 op_sel:[1,1,0]
	v_pk_fma_f16 v46, v47, v18, v46
	v_cvt_scalef32_pk_f16_fp4 v47, v51, 1.0
	v_pk_fma_f16 v47, v47, v18, v52
	v_cvt_scalef32_pk_f16_fp4 v50, v51, 1.0 op_sel:[1,0,0]
	v_cvt_scalef32_pk_f16_fp4 v52, v51, 1.0 op_sel:[0,1,0]
	v_cvt_scalef32_pk_f16_fp4 v51, v51, 1.0 op_sel:[1,1,0]
	v_pk_fma_f16 v50, v50, v18, v53
	v_pk_fma_f16 v52, v52, v18, v54
	v_pk_fma_f16 v14, v51, v18, v14
	s_waitcnt vmcnt(26)
	v_cvt_scalef32_pk_f16_fp4 v18, v48, 1.0
	v_pk_fma_f16 v15, v18, v19, v15
	v_cvt_scalef32_pk_f16_fp4 v18, v48, 1.0 op_sel:[1,0,0]
	v_pk_fma_f16 v16, v18, v19, v16
	v_cvt_scalef32_pk_f16_fp4 v18, v48, 1.0 op_sel:[0,1,0]
	v_pk_fma_f16 v17, v18, v19, v17
	v_cvt_scalef32_pk_f16_fp4 v18, v48, 1.0 op_sel:[1,1,0]
	v_pk_fma_f16 v18, v18, v19, v46
	v_cvt_scalef32_pk_f16_fp4 v46, v49, 1.0
	v_pk_fma_f16 v46, v46, v19, v47
	v_cvt_scalef32_pk_f16_fp4 v47, v49, 1.0 op_sel:[1,0,0]
	v_cvt_scalef32_pk_f16_fp4 v48, v49, 1.0 op_sel:[0,1,0]
	v_cvt_scalef32_pk_f16_fp4 v49, v49, 1.0 op_sel:[1,1,0]
	v_pk_fma_f16 v47, v47, v19, v50
	v_pk_fma_f16 v48, v48, v19, v52
	v_pk_fma_f16 v14, v49, v19, v14
	s_waitcnt vmcnt(25)
	v_cvt_scalef32_pk_f16_fp4 v19, v42, 1.0
	v_pk_fma_f16 v15, v19, v20, v15
	v_cvt_scalef32_pk_f16_fp4 v19, v42, 1.0 op_sel:[1,0,0]
	v_pk_fma_f16 v16, v19, v20, v16
	v_cvt_scalef32_pk_f16_fp4 v19, v42, 1.0 op_sel:[0,1,0]
	v_pk_fma_f16 v17, v19, v20, v17
	v_cvt_scalef32_pk_f16_fp4 v19, v42, 1.0 op_sel:[1,1,0]
	v_pk_fma_f16 v18, v19, v20, v18
	v_cvt_scalef32_pk_f16_fp4 v19, v43, 1.0
	v_pk_fma_f16 v19, v19, v20, v46
	v_cvt_scalef32_pk_f16_fp4 v42, v43, 1.0 op_sel:[1,0,0]
	v_cvt_scalef32_pk_f16_fp4 v46, v43, 1.0 op_sel:[0,1,0]
	v_cvt_scalef32_pk_f16_fp4 v43, v43, 1.0 op_sel:[1,1,0]
	v_pk_fma_f16 v42, v42, v20, v47
	v_pk_fma_f16 v46, v46, v20, v48
	v_pk_fma_f16 v14, v43, v20, v14
	s_waitcnt vmcnt(24)
	v_cvt_scalef32_pk_f16_fp4 v20, v44, 1.0
	v_pk_fma_f16 v15, v20, v21, v15
	v_cvt_scalef32_pk_f16_fp4 v20, v44, 1.0 op_sel:[1,0,0]
	v_pk_fma_f16 v16, v20, v21, v16
	v_cvt_scalef32_pk_f16_fp4 v20, v44, 1.0 op_sel:[0,1,0]
	v_pk_fma_f16 v17, v20, v21, v17
	v_cvt_scalef32_pk_f16_fp4 v20, v44, 1.0 op_sel:[1,1,0]
	v_pk_fma_f16 v18, v20, v21, v18
	v_cvt_scalef32_pk_f16_fp4 v20, v45, 1.0
	v_pk_fma_f16 v19, v20, v21, v19
	v_cvt_scalef32_pk_f16_fp4 v20, v45, 1.0 op_sel:[1,0,0]
	v_pk_fma_f16 v20, v20, v21, v42
	v_cvt_scalef32_pk_f16_fp4 v42, v45, 1.0 op_sel:[0,1,0]
	v_cvt_scalef32_pk_f16_fp4 v43, v45, 1.0 op_sel:[1,1,0]
	v_pk_fma_f16 v42, v42, v21, v46
	v_pk_fma_f16 v14, v43, v21, v14
	s_waitcnt vmcnt(23)
; #define PG_LD(T, TAB, ST) do { const int st_ = (ST); _Pragma("unroll") for (int k = 0; k < 16; ++k) { const int e = __builtin_amdgcn_readlane(st_ < 4 ? i0 : i1, (st_ * 16 + k) & 63); \
;       T[k] = __builtin_bit_cast(u32x2, __builtin_amdgcn_raw_buffer_load_b64(TAB, lane * 8, e * 512, 0)); } } while (0)
; DEVI void peer_gather_phase(const Params& p, int layer, char* lds) {
;     ...
; #pragma unroll 1
;     for (int b2 = 0; b2 < 4; ++b2) {
;       PG_LD(tb, srV, 2 * b2 + 1);
;       PG_AXPY(ta, 2 * b2);
;       if (b2 < 3) PG_LD(ta, srV, 2 * b2 + 2);
;       else if (hasn) {
; #pragma unroll
;         for (int k = 0; k < 16; ++k) { const int e = __builtin_amdgcn_readlane(i0n, k); ta[k] = __builtin_bit_cast(u32x2, __builtin_amdgcn_raw_buffer_load_b64(srU, lane * 8, e * 512, 0)); }
;       }
;       PG_AXPY(tb, 2 * b2 + 1);
;     }
	v_cvt_scalef32_pk_f16_fp4 v21, v40, 1.0
	s_waitcnt lgkmcnt(1)
	v_pk_fma_f16 v15, v21, v22, v15
	v_cvt_scalef32_pk_f16_fp4 v21, v40, 1.0 op_sel:[1,0,0]
	v_pk_fma_f16 v16, v21, v22, v16
	v_cvt_scalef32_pk_f16_fp4 v21, v40, 1.0 op_sel:[0,1,0]
	v_pk_fma_f16 v17, v21, v22, v17
	v_cvt_scalef32_pk_f16_fp4 v21, v40, 1.0 op_sel:[1,1,0]
	v_pk_fma_f16 v18, v21, v22, v18
	v_cvt_scalef32_pk_f16_fp4 v21, v41, 1.0
	v_pk_fma_f16 v19, v21, v22, v19
	v_cvt_scalef32_pk_f16_fp4 v21, v41, 1.0 op_sel:[1,0,0]
	v_pk_fma_f16 v20, v21, v22, v20
	v_cvt_scalef32_pk_f16_fp4 v21, v41, 1.0 op_sel:[0,1,0]
	v_cvt_scalef32_pk_f16_fp4 v40, v41, 1.0 op_sel:[1,1,0]
	v_pk_fma_f16 v21, v21, v22, v42
	v_pk_fma_f16 v14, v40, v22, v14
	s_waitcnt vmcnt(22)
	v_cvt_scalef32_pk_f16_fp4 v22, v38, 1.0
	v_pk_fma_f16 v15, v22, v23, v15
	v_cvt_scalef32_pk_f16_fp4 v22, v38, 1.0 op_sel:[1,0,0]
	v_pk_fma_f16 v16, v22, v23, v16
	v_cvt_scalef32_pk_f16_fp4 v22, v38, 1.0 op_sel:[0,1,0]
	v_pk_fma_f16 v17, v22, v23, v17
	v_cvt_scalef32_pk_f16_fp4 v22, v38, 1.0 op_sel:[1,1,0]
	v_pk_fma_f16 v18, v22, v23, v18
	v_cvt_scalef32_pk_f16_fp4 v22, v39, 1.0
	v_pk_fma_f16 v19, v22, v23, v19
	v_cvt_scalef32_pk_f16_fp4 v22, v39, 1.0 op_sel:[1,0,0]
	v_pk_fma_f16 v20, v22, v23, v20
	v_cvt_scalef32_pk_f16_fp4 v22, v39, 1.0 op_sel:[0,1,0]
	v_pk_fma_f16 v21, v22, v23, v21
	v_cvt_scalef32_pk_f16_fp4 v22, v39, 1.0 op_sel:[1,1,0]
	v_pk_fma_f16 v14, v22, v23, v14
	s_waitcnt vmcnt(21)
	v_cvt_scalef32_pk_f16_fp4 v22, v34, 1.0
	v_pk_fma_f16 v15, v22, v24, v15
	v_cvt_scalef32_pk_f16_fp4 v22, v34, 1.0 op_sel:[1,0,0]
	v_pk_fma_f16 v16, v22, v24, v16
	v_cvt_scalef32_pk_f16_fp4 v22, v34, 1.0 op_sel:[0,1,0]
	v_pk_fma_f16 v17, v22, v24, v17
	v_cvt_scalef32_pk_f16_fp4 v22, v34, 1.0 op_sel:[1,1,0]
	v_pk_fma_f16 v18, v22, v24, v18
	v_cvt_scalef32_pk_f16_fp4 v22, v35, 1.0
	v_pk_fma_f16 v19, v22, v24, v19
	v_cvt_scalef32_pk_f16_fp4 v22, v35, 1.0 op_sel:[1,0,0]
	v_pk_fma_f16 v20, v22, v24, v20
	v_cvt_scalef32_pk_f16_fp4 v22, v35, 1.0 op_sel:[0,1,0]
	v_pk_fma_f16 v21, v22, v24, v21
	v_cvt_scalef32_pk_f16_fp4 v22, v35, 1.0 op_sel:[1,1,0]
	v_pk_fma_f16 v14, v22, v24, v14
	s_waitcnt vmcnt(20)
	v_cvt_scalef32_pk_f16_fp4 v22, v36, 1.0
	v_pk_fma_f16 v15, v22, v25, v15
	v_cvt_scalef32_pk_f16_fp4 v22, v36, 1.0 op_sel:[1,0,0]
	v_pk_fma_f16 v16, v22, v25, v16
	v_cvt_scalef32_pk_f16_fp4 v22, v36, 1.0 op_sel:[0,1,0]
	v_pk_fma_f16 v17, v22, v25, v17
	v_cvt_scalef32_pk_f16_fp4 v22, v36, 1.0 op_sel:[1,1,0]
	v_pk_fma_f16 v18, v22, v25, v18
	v_cvt_scalef32_pk_f16_fp4 v22, v37, 1.0
	v_pk_fma_f16 v19, v22, v25, v19
	v_cvt_scalef32_pk_f16_fp4 v22, v37, 1.0 op_sel:[1,0,0]
	v_pk_fma_f16 v20, v22, v25, v20
	v_cvt_scalef32_pk_f16_fp4 v22, v37, 1.0 op_sel:[0,1,0]
	v_pk_fma_f16 v21, v22, v25, v21
	v_cvt_scalef32_pk_f16_fp4 v22, v37, 1.0 op_sel:[1,1,0]
	v_pk_fma_f16 v14, v22, v25, v14
	s_waitcnt vmcnt(19)
	v_cvt_scalef32_pk_f16_fp4 v22, v32, 1.0
	s_waitcnt lgkmcnt(0)
	v_pk_fma_f16 v15, v22, v10, v15
	v_cvt_scalef32_pk_f16_fp4 v22, v32, 1.0 op_sel:[1,0,0]
	v_pk_fma_f16 v16, v22, v10, v16
	v_cvt_scalef32_pk_f16_fp4 v22, v32, 1.0 op_sel:[0,1,0]
	v_pk_fma_f16 v17, v22, v10, v17
	v_cvt_scalef32_pk_f16_fp4 v22, v32, 1.0 op_sel:[1,1,0]
	v_pk_fma_f16 v18, v22, v10, v18
	v_cvt_scalef32_pk_f16_fp4 v22, v33, 1.0
	v_pk_fma_f16 v19, v22, v10, v19
	v_cvt_scalef32_pk_f16_fp4 v22, v33, 1.0 op_sel:[1,0,0]
	v_pk_fma_f16 v20, v22, v10, v20
	v_cvt_scalef32_pk_f16_fp4 v22, v33, 1.0 op_sel:[0,1,0]
	v_pk_fma_f16 v21, v22, v10, v21
	v_cvt_scalef32_pk_f16_fp4 v22, v33, 1.0 op_sel:[1,1,0]
	v_pk_fma_f16 v10, v22, v10, v14
	s_waitcnt vmcnt(18)
	v_cvt_scalef32_pk_f16_fp4 v14, v30, 1.0
	v_pk_fma_f16 v14, v14, v11, v15
	v_cvt_scalef32_pk_f16_fp4 v15, v30, 1.0 op_sel:[1,0,0]
	v_pk_fma_f16 v15, v15, v11, v16
	v_cvt_scalef32_pk_f16_fp4 v16, v30, 1.0 op_sel:[0,1,0]
	v_pk_fma_f16 v16, v16, v11, v17
	v_cvt_scalef32_pk_f16_fp4 v17, v30, 1.0 op_sel:[1,1,0]
	v_pk_fma_f16 v17, v17, v11, v18
	v_cvt_scalef32_pk_f16_fp4 v18, v31, 1.0
	v_pk_fma_f16 v18, v18, v11, v19
	v_cvt_scalef32_pk_f16_fp4 v19, v31, 1.0 op_sel:[1,0,0]
	v_pk_fma_f16 v19, v19, v11, v20
	v_cvt_scalef32_pk_f16_fp4 v20, v31, 1.0 op_sel:[0,1,0]
	v_pk_fma_f16 v20, v20, v11, v21
	v_cvt_scalef32_pk_f16_fp4 v21, v31, 1.0 op_sel:[1,1,0]
	v_pk_fma_f16 v10, v21, v11, v10
	s_waitcnt vmcnt(17)
	v_cvt_scalef32_pk_f16_fp4 v11, v26, 1.0
	v_pk_fma_f16 v11, v11, v12, v14
	v_cvt_scalef32_pk_f16_fp4 v14, v26, 1.0 op_sel:[1,0,0]
	v_pk_fma_f16 v14, v14, v12, v15
	v_cvt_scalef32_pk_f16_fp4 v15, v26, 1.0 op_sel:[0,1,0]
	v_pk_fma_f16 v15, v15, v12, v16
	v_cvt_scalef32_pk_f16_fp4 v16, v26, 1.0 op_sel:[1,1,0]
	v_pk_fma_f16 v16, v16, v12, v17
	v_cvt_scalef32_pk_f16_fp4 v17, v27, 1.0
	v_pk_fma_f16 v17, v17, v12, v18
	v_cvt_scalef32_pk_f16_fp4 v18, v27, 1.0 op_sel:[1,0,0]
	v_pk_fma_f16 v18, v18, v12, v19
	v_cvt_scalef32_pk_f16_fp4 v19, v27, 1.0 op_sel:[0,1,0]
	v_pk_fma_f16 v19, v19, v12, v20
	v_cvt_scalef32_pk_f16_fp4 v20, v27, 1.0 op_sel:[1,1,0]
	v_pk_fma_f16 v10, v20, v12, v10
	s_waitcnt vmcnt(16)
	v_cvt_scalef32_pk_f16_fp4 v12, v28, 1.0
	v_pk_fma_f16 v155, v12, v13, v11
	v_cvt_scalef32_pk_f16_fp4 v11, v28, 1.0 op_sel:[1,0,0]
	v_pk_fma_f16 v156, v11, v13, v14
	v_cvt_scalef32_pk_f16_fp4 v11, v28, 1.0 op_sel:[0,1,0]
	v_pk_fma_f16 v154, v11, v13, v15
	v_cvt_scalef32_pk_f16_fp4 v11, v28, 1.0 op_sel:[1,1,0]
	v_pk_fma_f16 v153, v11, v13, v16
	v_cvt_scalef32_pk_f16_fp4 v11, v29, 1.0
	v_pk_fma_f16 v152, v11, v13, v17
	v_cvt_scalef32_pk_f16_fp4 v11, v29, 1.0 op_sel:[1,0,0]
	v_pk_fma_f16 v151, v11, v13, v18
	v_cvt_scalef32_pk_f16_fp4 v11, v29, 1.0 op_sel:[0,1,0]
	v_pk_fma_f16 v150, v11, v13, v19
	v_cvt_scalef32_pk_f16_fp4 v11, v29, 1.0 op_sel:[1,1,0]
	s_add_i32 s1, s1, 1
	s_add_i32 s0, s0, 32
	v_pk_fma_f16 v149, v11, v13, v10
	s_cmpk_eq_i32 s0, 0x80
	v_add_u32_e32 v63, 0x80, v63
	s_cbranch_scc1 .LBB0_151
	s_branch .LBB0_141
